# MLA: alternate s_setprio between wave halves per half-iteration to balance barrier arrival
# speedup vs baseline: 1.0130x; 1.0096x over previous
; #define LAS __attribute__((address_space(3)))
; __global__ void __launch_bounds__(512) mega(Params p_unused) {
;   extern __shared__ __attribute__((aligned(16))) unsigned char smem[];
;   LAS unsigned char* lds = (LAS unsigned char*)smem;
;   cg::grid_group grid = cg::this_grid();
;   volatile LAS unsigned* xst = (volatile LAS unsigned*)(lds + 137216);
;   if (threadIdx.x == 0) { xst[0] = 0u; xst[1] = 0u; }
;   __syncthreads();
;   const XcdBarrier xb = xcd_barrier_post(((KP)__builtin_amdgcn_kernarg_segment_ptr())->bar, xst);
_Z4mega6Params:
	v_readfirstlane_b32 s32, v0
	s_nop 3
	s_bfe_u32 s32, s32, 0x10008
	s_mov_b64 s[90:91], s[0:1]
	s_load_dwordx2 s[52:53], s[0:1], 0xf8
	s_add_u32 s0, s90, 0xf8
	s_addc_u32 s1, s91, 0
	v_and_b32_e32 v194, 0x3ff, v0
	v_writelane_b32 v254, s0, 0
	v_cmp_eq_u32_e64 s[4:5], 0, v194
	s_nop 0
	v_writelane_b32 v254, s1, 1
	s_mov_b64 s[0:1], exec
	v_writelane_b32 v254, s4, 2
	s_nop 1
	v_writelane_b32 v254, s5, 3
	s_and_b64 s[4:5], s[0:1], s[4:5]
	s_mov_b64 exec, s[4:5]
	s_cbranch_execz .LBB0_2
	s_add_i32 s3, 0, 0x21800
	v_mov_b32_e32 v1, 0
	v_mov_b32_e32 v2, s3
	s_add_i32 s3, 0, 0x21804
	ds_write_b32 v2, v1
	v_mov_b32_e32 v2, s3
	ds_write_b32 v2, v1

; #define LAS __attribute__((address_space(3)))
; DI unsigned cvt_pk(float lo, float hi) { unsigned r; asm volatile("v_cvt_pk_bf16_f32 %0, %1, %2" : "=v"(r) : "v"(lo), "v"(hi)); return r; }
; DI float fexp2(float x) { return __builtin_amdgcn_exp2f(x); }
; template <int DK, int DV, int MODE> ...
;     ...
;   auto part2 = [&](f32x16 (&st)[2], int t) __attribute__((always_inline)) {
;     float ps0 = 0.f, ps1 = 0.f, ps2 = 0.f, ps3 = 0.f;
; #pragma unroll
;     for (int kb = 0; kb < 2; ++kb)
; #pragma unroll
;       for (int i = 0; i < 16; i += 4) {
;         const float p0 = fexp2(st[kb][i]), p1 = fexp2(st[kb][i + 1]), p2 = fexp2(st[kb][i + 2]), p3 = fexp2(st[kb][i + 3]);
;         st[kb][i] = p0; st[kb][i + 1] = p1; st[kb][i + 2] = p2; st[kb][i + 3] = p3; ps0 += p0; ps1 += p1; ps2 += p2; ps3 += p3;
;       }
;     lsum += (ps0 + ps1) + (ps2 + ps3);
;     bf16x8 pf[2][2];
; #pragma unroll
;     for (int kb = 0; kb < 2; ++kb)
; #pragma unroll
;       for (int s = 0; s < 2; ++s) { u32x4 pp; pp.x = cvt_pk(st[kb][8 * s], st[kb][8 * s + 1]); pp.y = cvt_pk(st[kb][8 * s + 2], st[kb][8 * s + 3]); pp.z = cvt_pk(st[kb][8 * s + 4], st[kb][8 * s + 5]); pp.w = cvt_pk(st[kb][8 * s + 6], st[kb][8 * s + 7]); pf[kb][s] = __builtin_bit_cast(bf16x8, pp); }
; #pragma unroll
;     for (int db = 0; db < DV / 32; ++db)
; #pragma unroll
;       for (int kb = 0; kb < 2; ++kb)
; #pragma unroll
;         for (int s = 0; s < 2; ++s) {
;           if (MODE == 1 && ((kb == 1 && s == 1 && cwu == 0) || (kb == 0 && s == 0 && cwu != 0))) continue;
;           const bf16x8 vf = *(const LAS bf16x8*)(lds + ATT_VB + (t & 3) * VBUF + (32 * db + r) * VSTR + (2 * kb + s) * 32 + hh * 16);
;           O[db] = __builtin_amdgcn_mfma_f32_32x32x16_bf16(vf, pf[kb][s], O[db], 0, 0, 0);
;         }
;   };
.LBB0_249:
	s_and_b32 s22, s20, 2
	s_mulk_i32 s22, 0x3400
	s_mulk_i32 s21, 0x2400
	v_add_u32_e32 v252, s22, v160
	ds_read_b128 v[196:199], v252
	ds_read_b128 v[200:203], v252 offset:32
	ds_read_b128 v[216:219], v252 offset:64
	ds_read_b128 v[230:233], v252 offset:96
	ds_read_b128 v[234:237], v252 offset:128
	ds_read_b128 v[244:247], v252 offset:160
	v_add_u32_e32 v243, s21, v163
	v_add_u32_e32 v0, 0x80, v167
	v_cmp_gt_i32_e32 vcc, s78, v0
	v_exp_f32_e32 v82, v82
	v_exp_f32_e32 v83, v83
	v_cndmask_b32_e32 v34, 0, v158, vcc
	v_cmp_lt_i32_e32 vcc, s77, v0
	v_exp_f32_e32 v84, v84
	v_exp_f32_e32 v85, v85
	v_cndmask_b32_e32 v0, v34, v159, vcc
	v_cmp_neq_f32_e32 vcc, s53, v143
	v_exp_f32_e32 v86, v86
	v_exp_f32_e32 v87, v87
	v_cndmask_b32_e32 v142, 0, v143, vcc
	v_sub_f32_e32 v34, v0, v142
	v_mov_b32_e32 v35, v34
	v_mov_b32_e32 v36, v34
	v_mov_b32_e32 v37, v34
	v_mov_b32_e32 v38, v34
	v_mov_b32_e32 v39, v34
	v_mov_b32_e32 v40, v34
	v_mov_b32_e32 v41, v34
	v_mov_b32_e32 v42, v34
	v_mov_b32_e32 v43, v34
	v_mov_b32_e32 v44, v34
	v_mov_b32_e32 v45, v34
	v_mov_b32_e32 v46, v34
	v_mov_b32_e32 v47, v34
	v_mov_b32_e32 v48, v34
	v_mov_b32_e32 v49, v34
	v_exp_f32_e32 v88, v88
	v_exp_f32_e32 v89, v89
	s_waitcnt lgkmcnt(5)
	v_mfma_f32_32x32x16_bf16 v[50:65], v[196:199], v[98:101], v[34:49]
	ds_read_b128 v[196:199], v252 offset:6656
	v_exp_f32_e32 v90, v90
	v_exp_f32_e32 v91, v91
	v_exp_f32_e32 v92, v92
	v_exp_f32_e32 v93, v93
	s_waitcnt lgkmcnt(5)
	v_mfma_f32_32x32x16_bf16 v[50:65], v[200:203], v[102:105], v[50:65]
	ds_read_b128 v[200:203], v252 offset:6688
	v_exp_f32_e32 v94, v94
	v_exp_f32_e32 v95, v95
	v_exp_f32_e32 v96, v96
	v_exp_f32_e32 v97, v97
	s_waitcnt lgkmcnt(5)
	v_mfma_f32_32x32x16_bf16 v[50:65], v[216:219], v[106:109], v[50:65]
	ds_read_b128 v[216:219], v252 offset:6720
	v_exp_f32_e32 v66, v66
	v_exp_f32_e32 v67, v67
	v_cvt_pk_bf16_f32 v168, v82, v83
	v_exp_f32_e32 v68, v68
	s_waitcnt lgkmcnt(5)
	v_mfma_f32_32x32x16_bf16 v[50:65], v[230:233], v[110:113], v[50:65]
	ds_read_b128 v[230:233], v252 offset:6752
	v_exp_f32_e32 v69, v69
	v_cvt_pk_bf16_f32 v169, v84, v85
	v_exp_f32_e32 v70, v70
	v_exp_f32_e32 v71, v71
	s_waitcnt lgkmcnt(5)
	v_mfma_f32_32x32x16_bf16 v[50:65], v[234:237], v[114:117], v[50:65]
	ds_read_b128 v[234:237], v252 offset:6784
	v_cvt_pk_bf16_f32 v170, v86, v87
	v_exp_f32_e32 v72, v72
	v_exp_f32_e32 v73, v73
	v_cvt_pk_bf16_f32 v171, v88, v89
	v_exp_f32_e32 v74, v74
	s_waitcnt lgkmcnt(5)
	v_mfma_f32_32x32x16_bf16 v[50:65], v[244:247], v[118:121], v[50:65]
	ds_read_b128 v[244:247], v252 offset:6816
	v_exp_f32_e32 v75, v75
	v_cvt_pk_bf16_f32 v180, v90, v91
	v_exp_f32_e32 v76, v76
	v_exp_f32_e32 v77, v77
	s_waitcnt lgkmcnt(5)
	v_mfma_f32_32x32x16_bf16 v[34:49], v[196:199], v[98:101], v[34:49]
	ds_read_b128 v[196:199], v243 offset:53248
	v_cvt_pk_bf16_f32 v181, v92, v93
	v_exp_f32_e32 v78, v78
	v_exp_f32_e32 v79, v79
	v_cvt_pk_bf16_f32 v182, v94, v95
	v_exp_f32_e32 v80, v80
	s_waitcnt lgkmcnt(5)
	v_mfma_f32_32x32x16_bf16 v[34:49], v[200:203], v[102:105], v[34:49]
	ds_read_b128 v[200:203], v243 offset:57856
	v_exp_f32_e32 v81, v81
	v_cvt_pk_bf16_f32 v183, v96, v97
	v_add_f32_e32 v172, v82, v86
	v_add_f32_e32 v173, v83, v87
	v_add_f32_e32 v176, v84, v88
	v_add_f32_e32 v179, v85, v89
	s_waitcnt lgkmcnt(5)
	v_mfma_f32_32x32x16_bf16 v[34:49], v[216:219], v[106:109], v[34:49]
	ds_read_b128 v[216:219], v243 offset:53280
	v_add_f32_e32 v172, v90, v172
	v_add_f32_e32 v173, v91, v173
	v_add_f32_e32 v176, v92, v176
	v_add_f32_e32 v179, v93, v179
	v_add_f32_e32 v172, v94, v172
	v_add_f32_e32 v173, v95, v173
	v_add_f32_e32 v176, v96, v176
	s_waitcnt lgkmcnt(5)
	v_mfma_f32_32x32x16_bf16 v[34:49], v[230:233], v[110:113], v[34:49]
	ds_read_b128 v[230:233], v243 offset:57888
	v_add_f32_e32 v179, v97, v179
	v_cvt_pk_bf16_f32 v184, v66, v67
	v_cvt_pk_bf16_f32 v185, v68, v69
	v_cvt_pk_bf16_f32 v186, v70, v71
	v_cvt_pk_bf16_f32 v187, v72, v73
	v_cvt_pk_bf16_f32 v188, v74, v75
	v_cvt_pk_bf16_f32 v189, v76, v77
	s_waitcnt lgkmcnt(5)
	v_mfma_f32_32x32x16_bf16 v[34:49], v[234:237], v[114:117], v[34:49]
	ds_read_b128 v[234:237], v243 offset:53312
	v_cvt_pk_bf16_f32 v190, v78, v79
	v_cvt_pk_bf16_f32 v191, v80, v81
	v_add_f32_e32 v172, v66, v172
	v_add_f32_e32 v173, v67, v173
	v_add_f32_e32 v176, v68, v176
	v_add_f32_e32 v179, v69, v179
	v_add_f32_e32 v172, v70, v172
	s_waitcnt lgkmcnt(5)
	v_mfma_f32_32x32x16_bf16 v[34:49], v[244:247], v[118:121], v[34:49]
	ds_read_b128 v[244:247], v243 offset:57920
	v_add_f32_e32 v173, v71, v173
	v_add_f32_e32 v176, v72, v176
	v_add_f32_e32 v179, v73, v179
	v_add_f32_e32 v172, v74, v172
	v_add_f32_e32 v173, v75, v173
	v_add_f32_e32 v176, v76, v176
	v_add_f32_e32 v179, v77, v179
	s_waitcnt lgkmcnt(5)
	v_mfma_f32_32x32x16_bf16 v[18:33], v[196:199], v[168:171], v[18:33]
	ds_read_b128 v[196:199], v243 offset:53344
	v_add_f32_e32 v172, v78, v172
	v_add_f32_e32 v173, v79, v173
	v_add_f32_e32 v176, v80, v176
	v_add_f32_e32 v179, v81, v179
	v_add_f32_e32 v172, v172, v173
	v_add_f32_e32 v176, v176, v179
	v_max3_f32 v248, v50, v51, v52
	s_waitcnt lgkmcnt(5)
	v_mfma_f32_32x32x16_bf16 v[2:17], v[200:203], v[168:171], v[2:17]
	ds_read_b128 v[200:203], v243 offset:57952
	v_max3_f32 v249, v57, v58, v59
	v_max3_f32 v248, v248, v53, v54
	v_max3_f32 v249, v249, v60, v61
	v_max3_f32 v248, v248, v55, v56
	v_max3_f32 v249, v249, v62, v63
	s_waitcnt lgkmcnt(5)
	v_mfma_f32_32x32x16_bf16 v[18:33], v[216:219], v[180:183], v[18:33]
	v_max3_f32 v250, v34, v35, v36
	v_max3_f32 v251, v41, v42, v43
	v_max3_f32 v250, v250, v37, v38
	v_max3_f32 v251, v251, v44, v45
	v_max3_f32 v250, v250, v39, v40
	v_max3_f32 v251, v251, v46, v47
	v_max3_f32 v248, v248, v249, v64
	s_waitcnt lgkmcnt(4)
	v_mfma_f32_32x32x16_bf16 v[2:17], v[230:233], v[180:183], v[2:17]
	v_max3_f32 v250, v250, v251, v48
	v_max3_f32 v248, v248, v65, v49
	v_max_f32_e32 v248, v248, v250
	v_mov_b32_e32 v249, v248
	s_waitcnt lgkmcnt(3)
	v_mfma_f32_32x32x16_bf16 v[18:33], v[234:237], v[184:187], v[18:33]
	s_waitcnt lgkmcnt(2)
	v_mfma_f32_32x32x16_bf16 v[2:17], v[244:247], v[184:187], v[2:17]
	s_waitcnt lgkmcnt(1)
	v_mfma_f32_32x32x16_bf16 v[18:33], v[196:199], v[188:191], v[18:33]
	s_waitcnt lgkmcnt(0)
	v_mfma_f32_32x32x16_bf16 v[2:17], v[200:203], v[188:191], v[2:17]
	v_add_f32_e32 v0, v172, v176
	v_add_f32_e32 v161, v161, v0
	v_permlane32_swap_b32 v248, v249
	v_max_f32_e32 v174, v248, v249
	s_setprio 0
	s_waitcnt lgkmcnt(0)
	s_barrier

.LBB0_251:
	s_cmp_eq_u32 s32, 0
	s_cbranch_scc1 .Lprio_a0
	s_setprio 3
	s_branch .Lprio_a1
.Lprio_a0:
	s_setprio 1
.Lprio_a1:
	s_add_i32 s22, s19, -2
	s_cmp_lt_u32 s22, s17
	s_cselect_b64 s[50:51], -1, 0
	s_cmp_ge_u32 s22, s17
	s_cbranch_scc1 .LBB0_257
	s_and_b32 s20, s22, 3
	s_mulk_i32 s20, 0x3400
	s_add_i32 s20, s20, 0
	s_and_saveexec_b64 s[48:49], s[44:45]
	s_cbranch_execz .LBB0_254
	v_add3_u32 v0, s20, v153, v154
	s_waitcnt vmcnt(0)
	ds_write_b128 v0, v[122:125]

; #define LAS __attribute__((address_space(3)))
; DI float fexp2(float x) { return __builtin_amdgcn_exp2f(x); }
; template <int DK, int DV, int MODE> ...
;     ...
;   auto part1 = [&](f32x16 (&st)[2], float mbase, int t) __attribute__((always_inline)) {
;     if (MODE == 0) {
;       const int d0 = rel0 + 64 * t;
;       if (!(d0 - 31 >= 91) && !(d0 + 63 <= -91)) {
;         const int rb_ = d0 - r + 4 * hh + 128;
; #pragma unroll
;         for (int kb = 0; kb < 2; ++kb)
; #pragma unroll
;           for (int i = 0; i < 16; ++i) { int idx = rb_ + 32 * kb + (i & 3) + 8 * (i >> 2); idx = idx < 0 ? 0 : (idx > 256 ? 256 : idx); st[kb][i] += lut[idx]; }
;       }
;     } else {
;       const int ka = ka0 + t;
;       const LAS unsigned char* rp = (const LAS unsigned char*)lut + (ka - ri + 7) * 128;
; #pragma unroll
;       for (int q = 0; q < 8; ++q) { unsigned wv = nacolp[q]; asm volatile("" : "+v"(wv));
; #pragma unroll
;     ...
;   auto part2 = [&](f32x16 (&st)[2], int t) __attribute__((always_inline)) {
;     float ps0 = 0.f, ps1 = 0.f, ps2 = 0.f, ps3 = 0.f;
; #pragma unroll
;     for (int kb = 0; kb < 2; ++kb)
; #pragma unroll
;       for (int i = 0; i < 16; i += 4) {
;         const float p0 = fexp2(st[kb][i]), p1 = fexp2(st[kb][i + 1]), p2 = fexp2(st[kb][i + 2]), p3 = fexp2(st[kb][i + 3]);
;         st[kb][i] = p0; st[kb][i + 1] = p1; st[kb][i + 2] = p2; st[kb][i + 3] = p3; ps0 += p0; ps1 += p1; ps2 += p2; ps3 += p3;
;       }
;     lsum += (ps0 + ps1) + (ps2 + ps3);
;     bf16x8 pf[2][2];
; #pragma unroll
;     for (int kb = 0; kb < 2; ++kb)
; #pragma unroll
;       for (int s = 0; s < 2; ++s) { u32x4 pp; pp.x = cvt_pk(st[kb][8 * s], st[kb][8 * s + 1]); pp.y = cvt_pk(st[kb][8 * s + 2], st[kb][8 * s + 3]); pp.z = cvt_pk(st[kb][8 * s + 4], st[kb][8 * s + 5]); pp.w = cvt_pk(st[kb][8 * s + 6], st[kb][8 * s + 7]); pf[kb][s] = __builtin_bit_cast(bf16x8, pp); }
; #pragma unroll
;     for (int db = 0; db < DV / 32; ++db)
; #pragma unroll
;       for (int kb = 0; kb < 2; ++kb)
; #pragma unroll
;         for (int s = 0; s < 2; ++s) {
;           if (MODE == 1 && ((kb == 1 && s == 1 && cwu == 0) || (kb == 0 && s == 0 && cwu != 0))) continue;
;           const bf16x8 vf = *(const LAS bf16x8*)(lds + ATT_VB + (t & 3) * VBUF + (32 * db + r) * VSTR + (2 * kb + s) * 32 + hh * 16);
;           O[db] = __builtin_amdgcn_mfma_f32_32x32x16_bf16(vf, pf[kb][s], O[db], 0, 0, 0);
;         }
;   };
.LBB0_273:
	s_add_i32 s25, s19, -4
	s_and_b32 s21, s25, 3
	s_mul_i32 s26, s21, 0x3400
	s_and_b32 s23, s23, 2
	v_add_u32_e32 v252, s26, v160
	s_mul_i32 s26, s23, 0x2400
	ds_read_b128 v[196:199], v252
	ds_read_b128 v[200:203], v252 offset:32
	ds_read_b128 v[216:219], v252 offset:64
	ds_read_b128 v[230:233], v252 offset:96
	ds_read_b128 v[234:237], v252 offset:128
	ds_read_b128 v[244:247], v252 offset:160
	v_add_u32_e32 v243, s26, v163
	v_add_u32_e32 v0, 64, v167
	v_cmp_gt_i32_e32 vcc, s78, v0
	v_exp_f32_e32 v50, v50
	v_exp_f32_e32 v51, v51
	v_cndmask_b32_e32 v66, 0, v158, vcc
	v_cmp_lt_i32_e32 vcc, s77, v0
	v_exp_f32_e32 v52, v52
	v_exp_f32_e32 v53, v53
	v_cndmask_b32_e32 v0, v66, v159, vcc
	v_cmp_neq_f32_e32 vcc, s53, v143
	v_exp_f32_e32 v54, v54
	v_exp_f32_e32 v55, v55
	v_cndmask_b32_e32 v144, 0, v143, vcc
	v_sub_f32_e32 v66, v0, v144
	v_mov_b32_e32 v67, v66
	v_mov_b32_e32 v68, v66
	v_mov_b32_e32 v69, v66
	v_mov_b32_e32 v70, v66
	v_mov_b32_e32 v71, v66
	v_mov_b32_e32 v72, v66
	v_mov_b32_e32 v73, v66
	v_mov_b32_e32 v74, v66
	v_mov_b32_e32 v75, v66
	v_mov_b32_e32 v76, v66
	v_mov_b32_e32 v77, v66
	v_mov_b32_e32 v78, v66
	v_mov_b32_e32 v79, v66
	v_mov_b32_e32 v80, v66
	v_mov_b32_e32 v81, v66
	v_exp_f32_e32 v56, v56
	v_exp_f32_e32 v57, v57
	s_waitcnt lgkmcnt(5)
	v_mfma_f32_32x32x16_bf16 v[82:97], v[196:199], v[98:101], v[66:81]
	ds_read_b128 v[196:199], v252 offset:6656
	v_exp_f32_e32 v58, v58
	v_exp_f32_e32 v59, v59
	v_exp_f32_e32 v60, v60
	v_exp_f32_e32 v61, v61
	s_waitcnt lgkmcnt(5)
	v_mfma_f32_32x32x16_bf16 v[82:97], v[200:203], v[102:105], v[82:97]
	ds_read_b128 v[200:203], v252 offset:6688
	v_exp_f32_e32 v62, v62
	v_exp_f32_e32 v63, v63
	v_exp_f32_e32 v64, v64
	v_exp_f32_e32 v65, v65
	s_waitcnt lgkmcnt(5)
	v_mfma_f32_32x32x16_bf16 v[82:97], v[216:219], v[106:109], v[82:97]
	ds_read_b128 v[216:219], v252 offset:6720
	v_exp_f32_e32 v34, v34
	v_exp_f32_e32 v35, v35
	v_cvt_pk_bf16_f32 v168, v50, v51
	v_exp_f32_e32 v36, v36
	s_waitcnt lgkmcnt(5)
	v_mfma_f32_32x32x16_bf16 v[82:97], v[230:233], v[110:113], v[82:97]
	ds_read_b128 v[230:233], v252 offset:6752
	v_exp_f32_e32 v37, v37
	v_cvt_pk_bf16_f32 v169, v52, v53
	v_exp_f32_e32 v38, v38
	v_exp_f32_e32 v39, v39
	s_waitcnt lgkmcnt(5)
	v_mfma_f32_32x32x16_bf16 v[82:97], v[234:237], v[114:117], v[82:97]
	ds_read_b128 v[234:237], v252 offset:6784
	v_cvt_pk_bf16_f32 v170, v54, v55
	v_exp_f32_e32 v40, v40
	v_exp_f32_e32 v41, v41
	v_cvt_pk_bf16_f32 v171, v56, v57
	v_exp_f32_e32 v42, v42
	s_waitcnt lgkmcnt(5)
	v_mfma_f32_32x32x16_bf16 v[82:97], v[244:247], v[118:121], v[82:97]
	ds_read_b128 v[244:247], v252 offset:6816
	v_exp_f32_e32 v43, v43
	v_cvt_pk_bf16_f32 v180, v58, v59
	v_exp_f32_e32 v44, v44
	v_exp_f32_e32 v45, v45
	s_waitcnt lgkmcnt(5)
	v_mfma_f32_32x32x16_bf16 v[66:81], v[196:199], v[98:101], v[66:81]
	ds_read_b128 v[196:199], v243 offset:53248
	v_cvt_pk_bf16_f32 v181, v60, v61
	v_exp_f32_e32 v46, v46
	v_exp_f32_e32 v47, v47
	v_cvt_pk_bf16_f32 v182, v62, v63
	v_exp_f32_e32 v48, v48
	s_waitcnt lgkmcnt(5)
	v_mfma_f32_32x32x16_bf16 v[66:81], v[200:203], v[102:105], v[66:81]
	ds_read_b128 v[200:203], v243 offset:57856
	v_exp_f32_e32 v49, v49
	v_cvt_pk_bf16_f32 v183, v64, v65
	v_add_f32_e32 v172, v50, v54
	v_add_f32_e32 v173, v51, v55
	v_add_f32_e32 v176, v52, v56
	v_add_f32_e32 v179, v53, v57
	s_waitcnt lgkmcnt(5)
	v_mfma_f32_32x32x16_bf16 v[66:81], v[216:219], v[106:109], v[66:81]
	ds_read_b128 v[216:219], v243 offset:53280
	v_add_f32_e32 v172, v58, v172
	v_add_f32_e32 v173, v59, v173
	v_add_f32_e32 v176, v60, v176
	v_add_f32_e32 v179, v61, v179
	v_add_f32_e32 v172, v62, v172
	v_add_f32_e32 v173, v63, v173
	v_add_f32_e32 v176, v64, v176
	s_waitcnt lgkmcnt(5)
	v_mfma_f32_32x32x16_bf16 v[66:81], v[230:233], v[110:113], v[66:81]
	ds_read_b128 v[230:233], v243 offset:57888
	v_add_f32_e32 v179, v65, v179
	v_cvt_pk_bf16_f32 v184, v34, v35
	v_cvt_pk_bf16_f32 v185, v36, v37
	v_cvt_pk_bf16_f32 v186, v38, v39
	v_cvt_pk_bf16_f32 v187, v40, v41
	v_cvt_pk_bf16_f32 v188, v42, v43
	v_cvt_pk_bf16_f32 v189, v44, v45
	s_waitcnt lgkmcnt(5)
	v_mfma_f32_32x32x16_bf16 v[66:81], v[234:237], v[114:117], v[66:81]
	ds_read_b128 v[234:237], v243 offset:53312
	v_cvt_pk_bf16_f32 v190, v46, v47
	v_cvt_pk_bf16_f32 v191, v48, v49
	v_add_f32_e32 v172, v34, v172
	v_add_f32_e32 v173, v35, v173
	v_add_f32_e32 v176, v36, v176
	v_add_f32_e32 v179, v37, v179
	v_add_f32_e32 v172, v38, v172
	s_waitcnt lgkmcnt(5)
	v_mfma_f32_32x32x16_bf16 v[66:81], v[244:247], v[118:121], v[66:81]
	ds_read_b128 v[244:247], v243 offset:57920
	v_add_f32_e32 v173, v39, v173
	v_add_f32_e32 v176, v40, v176
	v_add_f32_e32 v179, v41, v179
	v_add_f32_e32 v172, v42, v172
	v_add_f32_e32 v173, v43, v173
	v_add_f32_e32 v176, v44, v176
	v_add_f32_e32 v179, v45, v179
	s_waitcnt lgkmcnt(5)
	v_mfma_f32_32x32x16_bf16 v[18:33], v[196:199], v[168:171], v[18:33]
	ds_read_b128 v[196:199], v243 offset:53344
	v_add_f32_e32 v172, v46, v172
	v_add_f32_e32 v173, v47, v173
	v_add_f32_e32 v176, v48, v176
	v_add_f32_e32 v179, v49, v179
	v_add_f32_e32 v172, v172, v173
	v_add_f32_e32 v176, v176, v179
	v_max3_f32 v248, v82, v83, v84
	s_waitcnt lgkmcnt(5)
	v_mfma_f32_32x32x16_bf16 v[2:17], v[200:203], v[168:171], v[2:17]
	ds_read_b128 v[200:203], v243 offset:57952
	v_max3_f32 v249, v89, v90, v91
	v_max3_f32 v248, v248, v85, v86
	v_max3_f32 v249, v249, v92, v93
	v_max3_f32 v248, v248, v87, v88
	v_max3_f32 v249, v249, v94, v95
	s_waitcnt lgkmcnt(5)
	v_mfma_f32_32x32x16_bf16 v[18:33], v[216:219], v[180:183], v[18:33]
	v_max3_f32 v250, v66, v67, v68
	v_max3_f32 v251, v73, v74, v75
	v_max3_f32 v250, v250, v69, v70
	v_max3_f32 v251, v251, v76, v77
	v_max3_f32 v250, v250, v71, v72
	v_max3_f32 v251, v251, v78, v79
	v_max3_f32 v248, v248, v249, v96
	s_waitcnt lgkmcnt(4)
	v_mfma_f32_32x32x16_bf16 v[2:17], v[230:233], v[180:183], v[2:17]
	v_max3_f32 v250, v250, v251, v80
	v_max3_f32 v248, v248, v97, v81
	v_max_f32_e32 v248, v248, v250
	v_mov_b32_e32 v249, v248
	s_waitcnt lgkmcnt(3)
	v_mfma_f32_32x32x16_bf16 v[18:33], v[234:237], v[184:187], v[18:33]
	s_waitcnt lgkmcnt(2)
	v_mfma_f32_32x32x16_bf16 v[2:17], v[244:247], v[184:187], v[2:17]
	s_waitcnt lgkmcnt(1)
	v_mfma_f32_32x32x16_bf16 v[18:33], v[196:199], v[188:191], v[18:33]
	s_waitcnt lgkmcnt(0)
	v_mfma_f32_32x32x16_bf16 v[2:17], v[200:203], v[188:191], v[2:17]
	v_add_f32_e32 v0, v172, v176
	v_add_f32_e32 v161, v161, v0
	v_permlane32_swap_b32 v248, v249
	v_max_f32_e32 v174, v248, v249
	s_cmp_eq_u32 s32, 0
	s_cbranch_scc1 .Lprio_b0
	s_setprio 1
	s_branch .Lprio_b1
.Lprio_b0:
	s_setprio 3
.Lprio_b1:
	s_cmp_ge_u32 s25, s17
	s_cbranch_scc1 .LBB0_284
	v_cndmask_b32_e64 v0, 0, 1, s[66:67]
	v_cmp_ne_u32_e64 s[50:51], 1, v0
	s_andn2_b64 vcc, exec, s[66:67]
	s_cbranch_vccz .LBB0_285
	s_and_b64 vcc, exec, s[48:49]
	s_cbranch_vccz .LBB0_290
